# EpiRes epilogue (c_out + MLP-out L1) loads up front; stores drained before next unit
# speedup vs baseline: 1.0119x; 1.0119x over previous
.LBB0_1346:
	ds_read_b128 v[148:151], v158
	ds_read_b128 v[152:155], v158 offset:1024
	ds_read_b128 v[162:165], v158 offset:2048
	ds_read_b128 v[166:169], v158 offset:3072
	s_add_u32 s20, s38, 0xfff80080
	s_addc_u32 s21, s39, -1
	s_cmp_eq_u32 s61, 28
	s_cselect_b32 s21, s17, s21
	s_cselect_b32 s20, s57, s20
	s_cselect_b32 s45, s15, s60
	s_cselect_b32 s44, s58, s59
	v_lshl_add_u64 v[190:191], s[38:39], 0, v[136:137]
	s_add_i32 m0, s37, 0xc000
	ds_read_b128 v[170:173], v159
	ds_read_b128 v[174:177], v159 offset:1024
	ds_read_b128 v[178:181], v159 offset:2048
	ds_read_b128 v[182:185], v159 offset:3072
	ds_read_b128 v[186:189], v159 offset:4096
	ds_read_b128 v[196:199], v159 offset:5120
	ds_read_b128 v[200:203], v159 offset:6144
	ds_read_b128 v[204:207], v159 offset:7168
	global_load_lds_dwordx4 v[190:191], off
	v_lshl_add_u64 v[190:191], s[38:39], 0, v[138:139]
	s_add_i32 m0, s37, 0xe000
	s_nop 0
	global_load_lds_dwordx4 v[190:191], off
	s_waitcnt lgkmcnt(8)
	s_barrier
	s_waitcnt lgkmcnt(0)
	s_setprio 1
	s_waitcnt lgkmcnt(0)
	v_mfma_f32_16x16x32_bf16 v[124:127], v[148:151], v[170:173], v[124:127]
	v_mfma_f32_16x16x32_bf16 v[120:123], v[162:165], v[170:173], v[120:123]
	v_mfma_f32_16x16x32_bf16 v[108:111], v[148:151], v[178:181], v[108:111]
	v_mfma_f32_16x16x32_bf16 v[104:107], v[162:165], v[178:181], v[104:107]
	v_mfma_f32_16x16x32_bf16 v[92:95], v[148:151], v[186:189], v[92:95]
	v_mfma_f32_16x16x32_bf16 v[88:91], v[162:165], v[186:189], v[88:91]
	v_mfma_f32_16x16x32_bf16 v[76:79], v[148:151], v[200:203], v[76:79]
	v_mfma_f32_16x16x32_bf16 v[72:75], v[162:165], v[200:203], v[72:75]
	v_mfma_f32_16x16x32_bf16 v[124:127], v[152:155], v[174:177], v[124:127]
	v_mfma_f32_16x16x32_bf16 v[120:123], v[166:169], v[174:177], v[120:123]
	v_mfma_f32_16x16x32_bf16 v[108:111], v[152:155], v[182:185], v[108:111]
	v_mfma_f32_16x16x32_bf16 v[104:107], v[166:169], v[182:185], v[104:107]
	v_mfma_f32_16x16x32_bf16 v[92:95], v[152:155], v[196:199], v[92:95]
	v_mfma_f32_16x16x32_bf16 v[88:91], v[166:169], v[196:199], v[88:91]
	v_mfma_f32_16x16x32_bf16 v[76:79], v[152:155], v[204:207], v[76:79]
	v_mfma_f32_16x16x32_bf16 v[72:75], v[166:169], v[204:207], v[72:75]
	s_setprio 0
	s_barrier
	s_add_i32 s62, s53, s23
	v_lshl_add_u64 v[190:191], s[44:45], 0, v[132:133]
	s_mov_b32 m0, s62
	ds_read_b128 v[208:211], v160
	ds_read_b128 v[212:215], v160 offset:1024
	ds_read_b128 v[216:219], v160 offset:2048
	ds_read_b128 v[220:223], v160 offset:3072
	global_load_lds_dwordx4 v[190:191], off
	v_lshl_add_u64 v[224:225], s[44:45], 0, v[128:129]
	s_add_i32 m0, s62, 0x2000
	s_nop 0
	global_load_lds_dwordx4 v[224:225], off
	s_barrier
	s_waitcnt lgkmcnt(0)
	s_setprio 1
	s_waitcnt lgkmcnt(0)
	v_mfma_f32_16x16x32_bf16 v[116:119], v[208:211], v[170:173], v[116:119]
	v_mfma_f32_16x16x32_bf16 v[112:115], v[216:219], v[170:173], v[112:115]
	v_mfma_f32_16x16x32_bf16 v[100:103], v[208:211], v[178:181], v[100:103]
	v_mfma_f32_16x16x32_bf16 v[96:99], v[216:219], v[178:181], v[96:99]
	v_mfma_f32_16x16x32_bf16 v[84:87], v[208:211], v[186:189], v[84:87]
	v_mfma_f32_16x16x32_bf16 v[80:83], v[216:219], v[186:189], v[80:83]
	v_mfma_f32_16x16x32_bf16 v[68:71], v[208:211], v[200:203], v[68:71]
	v_mfma_f32_16x16x32_bf16 v[64:67], v[216:219], v[200:203], v[64:67]
	v_mfma_f32_16x16x32_bf16 v[116:119], v[212:215], v[174:177], v[116:119]
	v_mfma_f32_16x16x32_bf16 v[112:115], v[220:223], v[174:177], v[112:115]
	v_mfma_f32_16x16x32_bf16 v[100:103], v[212:215], v[182:185], v[100:103]
	v_mfma_f32_16x16x32_bf16 v[96:99], v[220:223], v[182:185], v[96:99]
	v_mfma_f32_16x16x32_bf16 v[84:87], v[212:215], v[196:199], v[84:87]
	v_mfma_f32_16x16x32_bf16 v[80:83], v[220:223], v[196:199], v[80:83]
	v_mfma_f32_16x16x32_bf16 v[68:71], v[212:215], v[204:207], v[68:71]
	v_mfma_f32_16x16x32_bf16 v[64:67], v[220:223], v[204:207], v[64:67]
	s_setprio 0
	s_mov_b32 m0, s37
	v_lshl_add_u64 v[226:227], s[20:21], 0, v[134:135]
	s_barrier
	ds_read_b128 v[170:173], v159 offset:16384
	ds_read_b128 v[174:177], v159 offset:17408
	ds_read_b128 v[178:181], v159 offset:18432
	ds_read_b128 v[182:185], v159 offset:19456
	ds_read_b128 v[186:189], v159 offset:20480
	ds_read_b128 v[196:199], v159 offset:21504
	ds_read_b128 v[200:203], v159 offset:22528
	ds_read_b128 v[204:207], v159 offset:23552
	global_load_lds_dwordx4 v[226:227], off
	v_lshl_add_u64 v[228:229], s[20:21], 0, v[130:131]
	s_mov_b32 m0, s47
	s_nop 0
	global_load_lds_dwordx4 v[228:229], off
	s_barrier
	s_waitcnt lgkmcnt(0)
	s_setprio 1
	s_waitcnt lgkmcnt(0)
	v_mfma_f32_16x16x32_bf16 v[60:63], v[148:151], v[170:173], v[60:63]
	v_mfma_f32_16x16x32_bf16 v[56:59], v[162:165], v[170:173], v[56:59]
	v_mfma_f32_16x16x32_bf16 v[44:47], v[148:151], v[178:181], v[44:47]
	v_mfma_f32_16x16x32_bf16 v[40:43], v[162:165], v[178:181], v[40:43]
	v_mfma_f32_16x16x32_bf16 v[28:31], v[148:151], v[186:189], v[28:31]
	v_mfma_f32_16x16x32_bf16 v[24:27], v[162:165], v[186:189], v[24:27]
	v_mfma_f32_16x16x32_bf16 v[12:15], v[148:151], v[200:203], v[12:15]
	v_mfma_f32_16x16x32_bf16 v[8:11], v[162:165], v[200:203], v[8:11]
	v_mfma_f32_16x16x32_bf16 v[60:63], v[152:155], v[174:177], v[60:63]
	v_mfma_f32_16x16x32_bf16 v[56:59], v[166:169], v[174:177], v[56:59]
	v_mfma_f32_16x16x32_bf16 v[44:47], v[152:155], v[182:185], v[44:47]
	v_mfma_f32_16x16x32_bf16 v[40:43], v[166:169], v[182:185], v[40:43]
	v_mfma_f32_16x16x32_bf16 v[28:31], v[152:155], v[196:199], v[28:31]
	v_mfma_f32_16x16x32_bf16 v[24:27], v[166:169], v[196:199], v[24:27]
	v_mfma_f32_16x16x32_bf16 v[12:15], v[152:155], v[204:207], v[12:15]
	v_mfma_f32_16x16x32_bf16 v[8:11], v[166:169], v[204:207], v[8:11]
	s_setprio 0
	s_barrier
	s_add_u32 s62, s44, 0x80000
	s_addc_u32 s63, s45, 0
	s_add_i32 s64, s55, s23
	v_lshl_add_u64 v[148:149], s[62:63], 0, v[132:133]
	s_mov_b32 m0, s64
	s_nop 0
	global_load_lds_dwordx4 v[148:149], off
	v_lshl_add_u64 v[148:149], s[62:63], 0, v[128:129]
	s_add_i32 m0, s64, 0x2000
	s_nop 0
	global_load_lds_dwordx4 v[148:149], off
	s_waitcnt vmcnt(6)
	s_barrier
	s_setprio 1
	v_mfma_f32_16x16x32_bf16 v[52:55], v[208:211], v[170:173], v[52:55]
	v_mfma_f32_16x16x32_bf16 v[48:51], v[216:219], v[170:173], v[48:51]
	v_mfma_f32_16x16x32_bf16 v[36:39], v[208:211], v[178:181], v[36:39]
	v_mfma_f32_16x16x32_bf16 v[32:35], v[216:219], v[178:181], v[32:35]
	v_mfma_f32_16x16x32_bf16 v[20:23], v[208:211], v[186:189], v[20:23]
	v_mfma_f32_16x16x32_bf16 v[16:19], v[216:219], v[186:189], v[16:19]
	v_mfma_f32_16x16x32_bf16 v[4:7], v[208:211], v[200:203], v[4:7]
	v_mfma_f32_16x16x32_bf16 v[0:3], v[216:219], v[200:203], v[0:3]
	v_mfma_f32_16x16x32_bf16 v[52:55], v[212:215], v[174:177], v[52:55]
	v_mfma_f32_16x16x32_bf16 v[48:51], v[220:223], v[174:177], v[48:51]
	v_mfma_f32_16x16x32_bf16 v[36:39], v[212:215], v[182:185], v[36:39]
	v_mfma_f32_16x16x32_bf16 v[32:35], v[220:223], v[182:185], v[32:35]
	v_mfma_f32_16x16x32_bf16 v[20:23], v[212:215], v[196:199], v[20:23]
	v_mfma_f32_16x16x32_bf16 v[16:19], v[220:223], v[196:199], v[16:19]
	v_mfma_f32_16x16x32_bf16 v[4:7], v[212:215], v[204:207], v[4:7]
	v_mfma_f32_16x16x32_bf16 v[0:3], v[220:223], v[204:207], v[0:3]
	s_setprio 0
	s_add_i32 s62, 0, 0x18000
	v_add_u32_e32 v161, s62, v147
	s_barrier
	ds_read_b128 v[148:151], v161
	ds_read_b128 v[152:155], v161 offset:1024
	ds_read_b128 v[162:165], v161 offset:2048
	ds_read_b128 v[166:169], v161 offset:3072
	s_add_u32 s20, s20, 0x80000
	s_addc_u32 s21, s21, 0
	s_mov_b32 m0, s48
	v_lshl_add_u64 v[208:209], s[20:21], 0, v[134:135]
	ds_read_b128 v[170:173], v159 offset:32768
	ds_read_b128 v[174:177], v159 offset:33792
	ds_read_b128 v[178:181], v159 offset:34816
	ds_read_b128 v[182:185], v159 offset:35840
	ds_read_b128 v[186:189], v159 offset:36864
	ds_read_b128 v[196:199], v159 offset:37888
	ds_read_b128 v[200:203], v159 offset:38912
	ds_read_b128 v[204:207], v159 offset:39936
	global_load_lds_dwordx4 v[208:209], off
	v_lshl_add_u64 v[208:209], s[20:21], 0, v[130:131]
	s_mov_b32 m0, s49
	s_nop 0
	global_load_lds_dwordx4 v[208:209], off
	s_waitcnt lgkmcnt(8)
	s_barrier
	s_waitcnt lgkmcnt(0)
	s_setprio 1
	s_waitcnt lgkmcnt(0)
	v_mfma_f32_16x16x32_bf16 v[124:127], v[148:151], v[170:173], v[124:127]
	v_mfma_f32_16x16x32_bf16 v[120:123], v[162:165], v[170:173], v[120:123]
	v_mfma_f32_16x16x32_bf16 v[108:111], v[148:151], v[178:181], v[108:111]
	v_mfma_f32_16x16x32_bf16 v[104:107], v[162:165], v[178:181], v[104:107]
	v_mfma_f32_16x16x32_bf16 v[92:95], v[148:151], v[186:189], v[92:95]
	v_mfma_f32_16x16x32_bf16 v[88:91], v[162:165], v[186:189], v[88:91]
	v_mfma_f32_16x16x32_bf16 v[76:79], v[148:151], v[200:203], v[76:79]
	v_mfma_f32_16x16x32_bf16 v[72:75], v[162:165], v[200:203], v[72:75]
	v_mfma_f32_16x16x32_bf16 v[124:127], v[152:155], v[174:177], v[124:127]
	v_mfma_f32_16x16x32_bf16 v[120:123], v[166:169], v[174:177], v[120:123]
	v_mfma_f32_16x16x32_bf16 v[108:111], v[152:155], v[182:185], v[108:111]
	v_mfma_f32_16x16x32_bf16 v[104:107], v[166:169], v[182:185], v[104:107]
	v_mfma_f32_16x16x32_bf16 v[92:95], v[152:155], v[196:199], v[92:95]
	v_mfma_f32_16x16x32_bf16 v[88:91], v[166:169], v[196:199], v[88:91]
	v_mfma_f32_16x16x32_bf16 v[76:79], v[152:155], v[204:207], v[76:79]
	v_mfma_f32_16x16x32_bf16 v[72:75], v[166:169], v[204:207], v[72:75]
	s_setprio 0
	s_barrier
	s_add_i32 s63, 0, 0x1c000
	s_add_i32 s20, s62, s23
	v_add_u32_e32 v161, s63, v147
	v_lshl_add_u64 v[190:191], v[190:191], 0, s[10:11]
	s_mov_b32 m0, s20
	ds_read_b128 v[208:211], v161
	ds_read_b128 v[212:215], v161 offset:1024
	ds_read_b128 v[216:219], v161 offset:2048
	ds_read_b128 v[220:223], v161 offset:3072
	global_load_lds_dwordx4 v[190:191], off
	v_lshl_add_u64 v[190:191], v[224:225], 0, s[10:11]
	s_add_i32 m0, s20, 0x2000
	s_nop 0
	global_load_lds_dwordx4 v[190:191], off
	s_barrier
	s_waitcnt lgkmcnt(0)
	s_setprio 1
	s_waitcnt lgkmcnt(0)
	v_mfma_f32_16x16x32_bf16 v[116:119], v[208:211], v[170:173], v[116:119]
	v_mfma_f32_16x16x32_bf16 v[112:115], v[216:219], v[170:173], v[112:115]
	v_mfma_f32_16x16x32_bf16 v[100:103], v[208:211], v[178:181], v[100:103]
	v_mfma_f32_16x16x32_bf16 v[96:99], v[216:219], v[178:181], v[96:99]
	v_mfma_f32_16x16x32_bf16 v[84:87], v[208:211], v[186:189], v[84:87]
	v_mfma_f32_16x16x32_bf16 v[80:83], v[216:219], v[186:189], v[80:83]
	v_mfma_f32_16x16x32_bf16 v[68:71], v[208:211], v[200:203], v[68:71]
	v_mfma_f32_16x16x32_bf16 v[64:67], v[216:219], v[200:203], v[64:67]
	v_mfma_f32_16x16x32_bf16 v[116:119], v[212:215], v[174:177], v[116:119]
	v_mfma_f32_16x16x32_bf16 v[112:115], v[220:223], v[174:177], v[112:115]
	v_mfma_f32_16x16x32_bf16 v[100:103], v[212:215], v[182:185], v[100:103]
	v_mfma_f32_16x16x32_bf16 v[96:99], v[220:223], v[182:185], v[96:99]
	v_mfma_f32_16x16x32_bf16 v[84:87], v[212:215], v[196:199], v[84:87]
	v_mfma_f32_16x16x32_bf16 v[80:83], v[220:223], v[196:199], v[80:83]
	v_mfma_f32_16x16x32_bf16 v[68:71], v[212:215], v[204:207], v[68:71]
	v_mfma_f32_16x16x32_bf16 v[64:67], v[220:223], v[204:207], v[64:67]
	s_setprio 0
	s_mov_b32 m0, s34
	v_lshl_add_u64 v[190:191], v[226:227], 0, s[10:11]
	s_barrier
	ds_read_b128 v[170:173], v159 offset:49152
	ds_read_b128 v[174:177], v159 offset:50176
	ds_read_b128 v[178:181], v159 offset:51200
	ds_read_b128 v[182:185], v159 offset:52224
	ds_read_b128 v[186:189], v159 offset:53248
	ds_read_b128 v[196:199], v159 offset:54272
	ds_read_b128 v[200:203], v159 offset:55296
	ds_read_b128 v[204:207], v159 offset:56320
	global_load_lds_dwordx4 v[190:191], off
	v_lshl_add_u64 v[190:191], v[228:229], 0, s[10:11]
	s_mov_b32 m0, s35
	s_nop 0
	global_load_lds_dwordx4 v[190:191], off
	s_barrier
	s_waitcnt lgkmcnt(0)
	s_setprio 1
	s_waitcnt lgkmcnt(0)
	v_mfma_f32_16x16x32_bf16 v[60:63], v[148:151], v[170:173], v[60:63]
	v_mfma_f32_16x16x32_bf16 v[56:59], v[162:165], v[170:173], v[56:59]
	v_mfma_f32_16x16x32_bf16 v[44:47], v[148:151], v[178:181], v[44:47]
	v_mfma_f32_16x16x32_bf16 v[40:43], v[162:165], v[178:181], v[40:43]
	v_mfma_f32_16x16x32_bf16 v[28:31], v[148:151], v[186:189], v[28:31]
	v_mfma_f32_16x16x32_bf16 v[24:27], v[162:165], v[186:189], v[24:27]
	v_mfma_f32_16x16x32_bf16 v[12:15], v[148:151], v[200:203], v[12:15]
	v_mfma_f32_16x16x32_bf16 v[8:11], v[162:165], v[200:203], v[8:11]
	v_mfma_f32_16x16x32_bf16 v[60:63], v[152:155], v[174:177], v[60:63]
	v_mfma_f32_16x16x32_bf16 v[56:59], v[166:169], v[174:177], v[56:59]
	v_mfma_f32_16x16x32_bf16 v[44:47], v[152:155], v[182:185], v[44:47]
	v_mfma_f32_16x16x32_bf16 v[40:43], v[166:169], v[182:185], v[40:43]
	v_mfma_f32_16x16x32_bf16 v[28:31], v[152:155], v[196:199], v[28:31]
	v_mfma_f32_16x16x32_bf16 v[24:27], v[166:169], v[196:199], v[24:27]
	v_mfma_f32_16x16x32_bf16 v[12:15], v[152:155], v[204:207], v[12:15]
	v_mfma_f32_16x16x32_bf16 v[8:11], v[166:169], v[204:207], v[8:11]
	s_setprio 0
	s_barrier
	s_add_u32 s20, s44, 0x80080
	s_addc_u32 s21, s45, 0
	s_add_i32 s44, s63, s23
	v_lshl_add_u64 v[148:149], s[20:21], 0, v[132:133]
	s_mov_b32 m0, s44
	s_nop 0
	global_load_lds_dwordx4 v[148:149], off
	v_lshl_add_u64 v[148:149], s[20:21], 0, v[128:129]
	s_add_i32 m0, s44, 0x2000
	s_nop 0
	global_load_lds_dwordx4 v[148:149], off
	s_waitcnt vmcnt(6)
	s_barrier
	s_setprio 1
	v_mfma_f32_16x16x32_bf16 v[52:55], v[208:211], v[170:173], v[52:55]
	v_mfma_f32_16x16x32_bf16 v[48:51], v[216:219], v[170:173], v[48:51]
	v_mfma_f32_16x16x32_bf16 v[36:39], v[208:211], v[178:181], v[36:39]
	v_mfma_f32_16x16x32_bf16 v[32:35], v[216:219], v[178:181], v[32:35]
	v_mfma_f32_16x16x32_bf16 v[20:23], v[208:211], v[186:189], v[20:23]
	v_mfma_f32_16x16x32_bf16 v[16:19], v[216:219], v[186:189], v[16:19]
	v_mfma_f32_16x16x32_bf16 v[4:7], v[208:211], v[200:203], v[4:7]
	v_mfma_f32_16x16x32_bf16 v[0:3], v[216:219], v[200:203], v[0:3]
	v_mfma_f32_16x16x32_bf16 v[52:55], v[212:215], v[174:177], v[52:55]
	v_mfma_f32_16x16x32_bf16 v[48:51], v[220:223], v[174:177], v[48:51]
	v_mfma_f32_16x16x32_bf16 v[36:39], v[212:215], v[182:185], v[36:39]
	v_mfma_f32_16x16x32_bf16 v[32:35], v[220:223], v[182:185], v[32:35]
	v_mfma_f32_16x16x32_bf16 v[20:23], v[212:215], v[196:199], v[20:23]
	v_mfma_f32_16x16x32_bf16 v[16:19], v[220:223], v[196:199], v[16:19]
	v_mfma_f32_16x16x32_bf16 v[4:7], v[212:215], v[204:207], v[4:7]
	v_mfma_f32_16x16x32_bf16 v[0:3], v[220:223], v[204:207], v[0:3]
	s_setprio 0
	s_add_i32 s61, s61, 2
	s_add_u32 s38, s38, 0x100
	s_addc_u32 s39, s39, 0
	s_add_u32 s59, s59, 0x100
	s_addc_u32 s60, s60, 0
	s_cmp_gt_u32 s61, 29
	s_barrier
	s_cbranch_scc0 .LBB0_1346
	s_lshl_b32 s15, s36, 8
	s_add_i32 s15, s15, s51
	v_or_b32_e32 v154, s15, v145
	s_add_i32 s17, s15, 0xffffe000
	v_lshl_or_b32 v150, s33, 8, v157
	s_lshr_b32 s17, s17, 12
	v_lshlrev_b32_e32 v148, 12, v154
	s_add_i32 s17, s17, 1
	s_cmp_gt_i32 s15, s56
	s_cselect_b32 s17, s17, 0
	s_mul_i32 s17, s17, s54
	v_lshl_add_u32 v148, v150, 1, v148
	s_add_u32 s20, s8, s17
	s_addc_u32 s21, s9, 0
	v_lshlrev_b32_e32 v149, 2, v150
	s_nop 0
	global_load_dwordx4 v[196:199], v149, s[20:21]
	global_load_dwordx4 v[200:203], v149, s[20:21] offset:16
	global_load_dwordx4 v[204:207], v149, s[20:21] offset:512
	global_load_dwordx4 v[208:211], v149, s[20:21] offset:528
	global_load_dwordx4 v[212:215], v148, s[74:75]
	global_load_dwordx4 v[216:219], v148, s[74:75] offset:256
	v_add_u32_e32 v151, 0x10000, v148
	global_load_dwordx4 v[220:223], v151, s[74:75]
	global_load_dwordx4 v[224:227], v151, s[74:75] offset:256
	v_add_u32_e32 v151, 0x20000, v148
	global_load_dwordx4 v[164:167], v151, s[74:75]
	global_load_dwordx4 v[168:171], v151, s[74:75] offset:256
	v_add_u32_e32 v151, 0x30000, v148
	global_load_dwordx4 v[172:175], v151, s[74:75]
	global_load_dwordx4 v[176:179], v151, s[74:75] offset:256
	s_mov_b32 s33, s14
	s_mov_b32 s36, s16
	s_mov_b64 s[44:45], s[24:25]
	s_mov_b64 s[38:39], s[18:19]
	s_waitcnt vmcnt(0)
	v_lshlrev_b32_e32 v180, 16, v212
	v_and_b32_e32 v181, 0xffff0000, v212
	v_lshlrev_b32_e32 v182, 16, v213
	v_and_b32_e32 v183, 0xffff0000, v213
	v_lshlrev_b32_e32 v184, 16, v214
	v_and_b32_e32 v185, 0xffff0000, v214
	v_lshlrev_b32_e32 v186, 16, v215
	v_and_b32_e32 v187, 0xffff0000, v215
	v_pk_fma_f32 v[124:125], v[124:125], v[196:197], v[180:181]
	v_pk_fma_f32 v[126:127], v[126:127], v[198:199], v[182:183]
	v_pk_fma_f32 v[120:121], v[120:121], v[200:201], v[184:185]
	v_pk_fma_f32 v[122:123], v[122:123], v[202:203], v[186:187]
	v_cvt_pk_bf16_f32 v123, v122, v123
	v_cvt_pk_bf16_f32 v122, v120, v121
	v_cvt_pk_bf16_f32 v121, v126, v127
	v_cvt_pk_bf16_f32 v120, v124, v125
	global_store_dwordx4 v148, v[120:123], s[74:75]
	v_lshlrev_b32_e32 v180, 16, v216
	v_and_b32_e32 v181, 0xffff0000, v216
	v_lshlrev_b32_e32 v182, 16, v217
	v_and_b32_e32 v183, 0xffff0000, v217
	v_lshlrev_b32_e32 v184, 16, v218
	v_and_b32_e32 v185, 0xffff0000, v218
	v_lshlrev_b32_e32 v186, 16, v219
	v_and_b32_e32 v187, 0xffff0000, v219
	v_pk_fma_f32 v[116:117], v[116:117], v[204:205], v[180:181]
	v_pk_fma_f32 v[118:119], v[118:119], v[206:207], v[182:183]
	v_pk_fma_f32 v[112:113], v[112:113], v[208:209], v[184:185]
	v_pk_fma_f32 v[114:115], v[114:115], v[210:211], v[186:187]
	v_cvt_pk_bf16_f32 v115, v114, v115
	v_cvt_pk_bf16_f32 v114, v112, v113
	v_cvt_pk_bf16_f32 v113, v118, v119
	v_cvt_pk_bf16_f32 v112, v116, v117
	global_store_dwordx4 v148, v[112:115], s[74:75] offset:256
	v_lshlrev_b32_e32 v180, 16, v220
	v_and_b32_e32 v181, 0xffff0000, v220
	v_lshlrev_b32_e32 v182, 16, v221
	v_and_b32_e32 v183, 0xffff0000, v221
	v_lshlrev_b32_e32 v184, 16, v222
	v_and_b32_e32 v185, 0xffff0000, v222
	v_lshlrev_b32_e32 v186, 16, v223
	v_and_b32_e32 v187, 0xffff0000, v223
	v_pk_fma_f32 v[108:109], v[108:109], v[196:197], v[180:181]
	v_pk_fma_f32 v[110:111], v[110:111], v[198:199], v[182:183]
	v_pk_fma_f32 v[104:105], v[104:105], v[200:201], v[184:185]
	v_pk_fma_f32 v[106:107], v[106:107], v[202:203], v[186:187]
	v_cvt_pk_bf16_f32 v107, v106, v107
	v_cvt_pk_bf16_f32 v106, v104, v105
	v_cvt_pk_bf16_f32 v105, v110, v111
	v_cvt_pk_bf16_f32 v104, v108, v109
	v_add_u32_e32 v151, 0x10000, v148
	global_store_dwordx4 v151, v[104:107], s[74:75]
	v_lshlrev_b32_e32 v180, 16, v224
	v_and_b32_e32 v181, 0xffff0000, v224
	v_lshlrev_b32_e32 v182, 16, v225
	v_and_b32_e32 v183, 0xffff0000, v225
	v_lshlrev_b32_e32 v184, 16, v226
	v_and_b32_e32 v185, 0xffff0000, v226
	v_lshlrev_b32_e32 v186, 16, v227
	v_and_b32_e32 v187, 0xffff0000, v227
	v_pk_fma_f32 v[100:101], v[100:101], v[204:205], v[180:181]
	v_pk_fma_f32 v[102:103], v[102:103], v[206:207], v[182:183]
	v_pk_fma_f32 v[96:97], v[96:97], v[208:209], v[184:185]
	v_pk_fma_f32 v[98:99], v[98:99], v[210:211], v[186:187]
	v_cvt_pk_bf16_f32 v99, v98, v99
	v_cvt_pk_bf16_f32 v98, v96, v97
	v_cvt_pk_bf16_f32 v97, v102, v103
	v_cvt_pk_bf16_f32 v96, v100, v101
	v_add_u32_e32 v151, 0x10000, v148
	global_store_dwordx4 v151, v[96:99], s[74:75] offset:256
	v_add_u32_e32 v151, 0x80000, v148
	global_load_dwordx4 v[212:215], v151, s[74:75]
	global_load_dwordx4 v[216:219], v151, s[74:75] offset:256
	v_add_u32_e32 v151, 0x90000, v148
	global_load_dwordx4 v[220:223], v151, s[74:75]
	global_load_dwordx4 v[224:227], v151, s[74:75] offset:256
	v_lshlrev_b32_e32 v180, 16, v164
	v_and_b32_e32 v181, 0xffff0000, v164
	v_lshlrev_b32_e32 v182, 16, v165
	v_and_b32_e32 v183, 0xffff0000, v165
	v_lshlrev_b32_e32 v184, 16, v166
	v_and_b32_e32 v185, 0xffff0000, v166
	v_lshlrev_b32_e32 v186, 16, v167
	v_and_b32_e32 v187, 0xffff0000, v167
	v_pk_fma_f32 v[92:93], v[92:93], v[196:197], v[180:181]
	v_pk_fma_f32 v[94:95], v[94:95], v[198:199], v[182:183]
	v_pk_fma_f32 v[88:89], v[88:89], v[200:201], v[184:185]
	v_pk_fma_f32 v[90:91], v[90:91], v[202:203], v[186:187]
	v_cvt_pk_bf16_f32 v91, v90, v91
	v_cvt_pk_bf16_f32 v90, v88, v89
	v_cvt_pk_bf16_f32 v89, v94, v95
	v_cvt_pk_bf16_f32 v88, v92, v93
	v_add_u32_e32 v151, 0x20000, v148
	global_store_dwordx4 v151, v[88:91], s[74:75]
	v_lshlrev_b32_e32 v180, 16, v168
	v_and_b32_e32 v181, 0xffff0000, v168
	v_lshlrev_b32_e32 v182, 16, v169
	v_and_b32_e32 v183, 0xffff0000, v169
	v_lshlrev_b32_e32 v184, 16, v170
	v_and_b32_e32 v185, 0xffff0000, v170
	v_lshlrev_b32_e32 v186, 16, v171
	v_and_b32_e32 v187, 0xffff0000, v171
	v_pk_fma_f32 v[84:85], v[84:85], v[204:205], v[180:181]
	v_pk_fma_f32 v[86:87], v[86:87], v[206:207], v[182:183]
	v_pk_fma_f32 v[80:81], v[80:81], v[208:209], v[184:185]
	v_pk_fma_f32 v[82:83], v[82:83], v[210:211], v[186:187]
	v_cvt_pk_bf16_f32 v83, v82, v83
	v_cvt_pk_bf16_f32 v82, v80, v81
	v_cvt_pk_bf16_f32 v81, v86, v87
	v_cvt_pk_bf16_f32 v80, v84, v85
	v_add_u32_e32 v151, 0x20000, v148
	global_store_dwordx4 v151, v[80:83], s[74:75] offset:256
	v_lshlrev_b32_e32 v180, 16, v172
	v_and_b32_e32 v181, 0xffff0000, v172
	v_lshlrev_b32_e32 v182, 16, v173
	v_and_b32_e32 v183, 0xffff0000, v173
	v_lshlrev_b32_e32 v184, 16, v174
	v_and_b32_e32 v185, 0xffff0000, v174
	v_lshlrev_b32_e32 v186, 16, v175
	v_and_b32_e32 v187, 0xffff0000, v175
	v_pk_fma_f32 v[76:77], v[76:77], v[196:197], v[180:181]
	v_pk_fma_f32 v[78:79], v[78:79], v[198:199], v[182:183]
	v_pk_fma_f32 v[72:73], v[72:73], v[200:201], v[184:185]
	v_pk_fma_f32 v[74:75], v[74:75], v[202:203], v[186:187]
	v_cvt_pk_bf16_f32 v75, v74, v75
	v_cvt_pk_bf16_f32 v74, v72, v73
	v_cvt_pk_bf16_f32 v73, v78, v79
	v_cvt_pk_bf16_f32 v72, v76, v77
	v_add_u32_e32 v151, 0x30000, v148
	global_store_dwordx4 v151, v[72:75], s[74:75]
	v_lshlrev_b32_e32 v180, 16, v176
	v_and_b32_e32 v181, 0xffff0000, v176
	v_lshlrev_b32_e32 v182, 16, v177
	v_and_b32_e32 v183, 0xffff0000, v177
	v_lshlrev_b32_e32 v184, 16, v178
	v_and_b32_e32 v185, 0xffff0000, v178
	v_lshlrev_b32_e32 v186, 16, v179
	v_and_b32_e32 v187, 0xffff0000, v179
	v_pk_fma_f32 v[68:69], v[68:69], v[204:205], v[180:181]
	v_pk_fma_f32 v[70:71], v[70:71], v[206:207], v[182:183]
	v_pk_fma_f32 v[64:65], v[64:65], v[208:209], v[184:185]
	v_pk_fma_f32 v[66:67], v[66:67], v[210:211], v[186:187]
	v_cvt_pk_bf16_f32 v67, v66, v67
	v_cvt_pk_bf16_f32 v66, v64, v65
	v_cvt_pk_bf16_f32 v65, v70, v71
	v_cvt_pk_bf16_f32 v64, v68, v69
	v_add_u32_e32 v151, 0x30000, v148
	global_store_dwordx4 v151, v[64:67], s[74:75] offset:256
	v_add_u32_e32 v151, 0xa0000, v148
	global_load_dwordx4 v[164:167], v151, s[74:75]
	global_load_dwordx4 v[168:171], v151, s[74:75] offset:256
	v_add_u32_e32 v151, 0xb0000, v148
	global_load_dwordx4 v[172:175], v151, s[74:75]
	global_load_dwordx4 v[176:179], v151, s[74:75] offset:256
	s_waitcnt vmcnt(0)
	v_lshlrev_b32_e32 v180, 16, v212
	v_and_b32_e32 v181, 0xffff0000, v212
	v_lshlrev_b32_e32 v182, 16, v213
	v_and_b32_e32 v183, 0xffff0000, v213
	v_lshlrev_b32_e32 v184, 16, v214
	v_and_b32_e32 v185, 0xffff0000, v214
	v_lshlrev_b32_e32 v186, 16, v215
	v_and_b32_e32 v187, 0xffff0000, v215
	v_pk_fma_f32 v[60:61], v[60:61], v[196:197], v[180:181]
	v_pk_fma_f32 v[62:63], v[62:63], v[198:199], v[182:183]
	v_pk_fma_f32 v[56:57], v[56:57], v[200:201], v[184:185]
	v_pk_fma_f32 v[58:59], v[58:59], v[202:203], v[186:187]
	v_cvt_pk_bf16_f32 v59, v58, v59
	v_cvt_pk_bf16_f32 v58, v56, v57
	v_cvt_pk_bf16_f32 v57, v62, v63
	v_cvt_pk_bf16_f32 v56, v60, v61
	v_add_u32_e32 v151, 0x80000, v148
	global_store_dwordx4 v151, v[56:59], s[74:75]
	v_lshlrev_b32_e32 v180, 16, v216
	v_and_b32_e32 v181, 0xffff0000, v216
	v_lshlrev_b32_e32 v182, 16, v217
	v_and_b32_e32 v183, 0xffff0000, v217
	v_lshlrev_b32_e32 v184, 16, v218
	v_and_b32_e32 v185, 0xffff0000, v218
	v_lshlrev_b32_e32 v186, 16, v219
	v_and_b32_e32 v187, 0xffff0000, v219
	v_pk_fma_f32 v[52:53], v[52:53], v[204:205], v[180:181]
	v_pk_fma_f32 v[54:55], v[54:55], v[206:207], v[182:183]
	v_pk_fma_f32 v[48:49], v[48:49], v[208:209], v[184:185]
	v_pk_fma_f32 v[50:51], v[50:51], v[210:211], v[186:187]
	v_cvt_pk_bf16_f32 v51, v50, v51
	v_cvt_pk_bf16_f32 v50, v48, v49
	v_cvt_pk_bf16_f32 v49, v54, v55
	v_cvt_pk_bf16_f32 v48, v52, v53
	v_add_u32_e32 v151, 0x80000, v148
	global_store_dwordx4 v151, v[48:51], s[74:75] offset:256
	v_lshlrev_b32_e32 v180, 16, v220
	v_and_b32_e32 v181, 0xffff0000, v220
	v_lshlrev_b32_e32 v182, 16, v221
	v_and_b32_e32 v183, 0xffff0000, v221
	v_lshlrev_b32_e32 v184, 16, v222
	v_and_b32_e32 v185, 0xffff0000, v222
	v_lshlrev_b32_e32 v186, 16, v223
	v_and_b32_e32 v187, 0xffff0000, v223
	v_pk_fma_f32 v[44:45], v[44:45], v[196:197], v[180:181]
	v_pk_fma_f32 v[46:47], v[46:47], v[198:199], v[182:183]
	v_pk_fma_f32 v[40:41], v[40:41], v[200:201], v[184:185]
	v_pk_fma_f32 v[42:43], v[42:43], v[202:203], v[186:187]
	v_cvt_pk_bf16_f32 v43, v42, v43
	v_cvt_pk_bf16_f32 v42, v40, v41
	v_cvt_pk_bf16_f32 v41, v46, v47
	v_cvt_pk_bf16_f32 v40, v44, v45
	v_add_u32_e32 v151, 0x90000, v148
	global_store_dwordx4 v151, v[40:43], s[74:75]
	v_lshlrev_b32_e32 v180, 16, v224
	v_and_b32_e32 v181, 0xffff0000, v224
	v_lshlrev_b32_e32 v182, 16, v225
	v_and_b32_e32 v183, 0xffff0000, v225
	v_lshlrev_b32_e32 v184, 16, v226
	v_and_b32_e32 v185, 0xffff0000, v226
	v_lshlrev_b32_e32 v186, 16, v227
	v_and_b32_e32 v187, 0xffff0000, v227
	v_pk_fma_f32 v[36:37], v[36:37], v[204:205], v[180:181]
	v_pk_fma_f32 v[38:39], v[38:39], v[206:207], v[182:183]
	v_pk_fma_f32 v[32:33], v[32:33], v[208:209], v[184:185]
	v_pk_fma_f32 v[34:35], v[34:35], v[210:211], v[186:187]
	v_cvt_pk_bf16_f32 v35, v34, v35
	v_cvt_pk_bf16_f32 v34, v32, v33
	v_cvt_pk_bf16_f32 v33, v38, v39
	v_cvt_pk_bf16_f32 v32, v36, v37
	v_add_u32_e32 v151, 0x90000, v148
	global_store_dwordx4 v151, v[32:35], s[74:75] offset:256
	v_lshlrev_b32_e32 v180, 16, v164
	v_and_b32_e32 v181, 0xffff0000, v164
	v_lshlrev_b32_e32 v182, 16, v165
	v_and_b32_e32 v183, 0xffff0000, v165
	v_lshlrev_b32_e32 v184, 16, v166
	v_and_b32_e32 v185, 0xffff0000, v166
	v_lshlrev_b32_e32 v186, 16, v167
	v_and_b32_e32 v187, 0xffff0000, v167
	v_pk_fma_f32 v[28:29], v[28:29], v[196:197], v[180:181]
	v_pk_fma_f32 v[30:31], v[30:31], v[198:199], v[182:183]
	v_pk_fma_f32 v[24:25], v[24:25], v[200:201], v[184:185]
	v_pk_fma_f32 v[26:27], v[26:27], v[202:203], v[186:187]
	v_cvt_pk_bf16_f32 v27, v26, v27
	v_cvt_pk_bf16_f32 v26, v24, v25
	v_cvt_pk_bf16_f32 v25, v30, v31
	v_cvt_pk_bf16_f32 v24, v28, v29
	v_add_u32_e32 v151, 0xa0000, v148
	global_store_dwordx4 v151, v[24:27], s[74:75]
	v_lshlrev_b32_e32 v180, 16, v168
	v_and_b32_e32 v181, 0xffff0000, v168
	v_lshlrev_b32_e32 v182, 16, v169
	v_and_b32_e32 v183, 0xffff0000, v169
	v_lshlrev_b32_e32 v184, 16, v170
	v_and_b32_e32 v185, 0xffff0000, v170
	v_lshlrev_b32_e32 v186, 16, v171
	v_and_b32_e32 v187, 0xffff0000, v171
	v_pk_fma_f32 v[20:21], v[20:21], v[204:205], v[180:181]
	v_pk_fma_f32 v[22:23], v[22:23], v[206:207], v[182:183]
	v_pk_fma_f32 v[16:17], v[16:17], v[208:209], v[184:185]
	v_pk_fma_f32 v[18:19], v[18:19], v[210:211], v[186:187]
	v_cvt_pk_bf16_f32 v19, v18, v19
	v_cvt_pk_bf16_f32 v18, v16, v17
	v_cvt_pk_bf16_f32 v17, v22, v23
	v_cvt_pk_bf16_f32 v16, v20, v21
	v_add_u32_e32 v151, 0xa0000, v148
	global_store_dwordx4 v151, v[16:19], s[74:75] offset:256
	v_lshlrev_b32_e32 v180, 16, v172
	v_and_b32_e32 v181, 0xffff0000, v172
	v_lshlrev_b32_e32 v182, 16, v173
	v_and_b32_e32 v183, 0xffff0000, v173
	v_lshlrev_b32_e32 v184, 16, v174
	v_and_b32_e32 v185, 0xffff0000, v174
	v_lshlrev_b32_e32 v186, 16, v175
	v_and_b32_e32 v187, 0xffff0000, v175
	v_pk_fma_f32 v[12:13], v[12:13], v[196:197], v[180:181]
	v_pk_fma_f32 v[14:15], v[14:15], v[198:199], v[182:183]
	v_pk_fma_f32 v[8:9], v[8:9], v[200:201], v[184:185]
	v_pk_fma_f32 v[10:11], v[10:11], v[202:203], v[186:187]
	v_cvt_pk_bf16_f32 v11, v10, v11
	v_cvt_pk_bf16_f32 v10, v8, v9
	v_cvt_pk_bf16_f32 v9, v14, v15
	v_cvt_pk_bf16_f32 v8, v12, v13
	v_add_u32_e32 v151, 0xb0000, v148
	global_store_dwordx4 v151, v[8:11], s[74:75]
	v_lshlrev_b32_e32 v180, 16, v176
	v_and_b32_e32 v181, 0xffff0000, v176
	v_lshlrev_b32_e32 v182, 16, v177
	v_and_b32_e32 v183, 0xffff0000, v177
	v_lshlrev_b32_e32 v184, 16, v178
	v_and_b32_e32 v185, 0xffff0000, v178
	v_lshlrev_b32_e32 v186, 16, v179
	v_and_b32_e32 v187, 0xffff0000, v179
	v_pk_fma_f32 v[4:5], v[4:5], v[204:205], v[180:181]
	v_pk_fma_f32 v[6:7], v[6:7], v[206:207], v[182:183]
	v_pk_fma_f32 v[0:1], v[0:1], v[208:209], v[184:185]
	v_pk_fma_f32 v[2:3], v[2:3], v[210:211], v[186:187]
	v_cvt_pk_bf16_f32 v3, v2, v3
	v_cvt_pk_bf16_f32 v2, v0, v1
	v_cvt_pk_bf16_f32 v1, v6, v7
	v_cvt_pk_bf16_f32 v0, v4, v5
	v_add_u32_e32 v151, 0xb0000, v148
	global_store_dwordx4 v151, v[0:3], s[74:75] offset:256
	s_waitcnt vmcnt(0)
	s_and_b64 vcc, exec, s[0:1]
	s_cbranch_vccz .LBB0_1343
	s_waitcnt vmcnt(0)
	s_cmpk_gt_u32 s12, 0xff
	s_cbranch_scc1 .LBB0_1350
	s_barrier

.LBB0_1433:
	ds_read_b128 v[148:151], v158
	ds_read_b128 v[152:155], v158 offset:1024
	ds_read_b128 v[162:165], v158 offset:2048
	ds_read_b128 v[166:169], v158 offset:3072
	s_add_u32 s20, s26, 0xffe00080
	s_addc_u32 s21, s27, -1
	s_cmpk_eq_i32 s53, 0x7c
	s_cselect_b32 s21, s15, s21
	s_cselect_b32 s20, s49, s20
	s_cselect_b32 s31, s11, s52
	s_cselect_b32 s30, s50, s51
	v_lshl_add_u64 v[204:205], s[26:27], 0, v[136:137]
	s_add_i32 m0, s25, 0xc000
	ds_read_b128 v[170:173], v159
	ds_read_b128 v[174:177], v159 offset:1024
	ds_read_b128 v[178:181], v159 offset:2048
	ds_read_b128 v[182:185], v159 offset:3072
	ds_read_b128 v[186:189], v159 offset:4096
	ds_read_b128 v[190:193], v159 offset:5120
	ds_read_b128 v[196:199], v159 offset:6144
	ds_read_b128 v[200:203], v159 offset:7168
	global_load_lds_dwordx4 v[204:205], off
	v_lshl_add_u64 v[204:205], s[26:27], 0, v[138:139]
	s_add_i32 m0, s25, 0xe000
	s_nop 0
	global_load_lds_dwordx4 v[204:205], off
	s_waitcnt lgkmcnt(8)
	s_barrier
	s_waitcnt lgkmcnt(0)
	s_setprio 1
	s_waitcnt lgkmcnt(0)
	v_mfma_f32_16x16x32_bf16 v[124:127], v[148:151], v[170:173], v[124:127]
	v_mfma_f32_16x16x32_bf16 v[120:123], v[162:165], v[170:173], v[120:123]
	v_mfma_f32_16x16x32_bf16 v[108:111], v[148:151], v[178:181], v[108:111]
	v_mfma_f32_16x16x32_bf16 v[104:107], v[162:165], v[178:181], v[104:107]
	v_mfma_f32_16x16x32_bf16 v[92:95], v[148:151], v[186:189], v[92:95]
	v_mfma_f32_16x16x32_bf16 v[88:91], v[162:165], v[186:189], v[88:91]
	v_mfma_f32_16x16x32_bf16 v[76:79], v[148:151], v[196:199], v[76:79]
	v_mfma_f32_16x16x32_bf16 v[72:75], v[162:165], v[196:199], v[72:75]
	v_mfma_f32_16x16x32_bf16 v[124:127], v[152:155], v[174:177], v[124:127]
	v_mfma_f32_16x16x32_bf16 v[120:123], v[166:169], v[174:177], v[120:123]
	v_mfma_f32_16x16x32_bf16 v[108:111], v[152:155], v[182:185], v[108:111]
	v_mfma_f32_16x16x32_bf16 v[104:107], v[166:169], v[182:185], v[104:107]
	v_mfma_f32_16x16x32_bf16 v[92:95], v[152:155], v[190:193], v[92:95]
	v_mfma_f32_16x16x32_bf16 v[88:91], v[166:169], v[190:193], v[88:91]
	v_mfma_f32_16x16x32_bf16 v[76:79], v[152:155], v[200:203], v[76:79]
	v_mfma_f32_16x16x32_bf16 v[72:75], v[166:169], v[200:203], v[72:75]
	s_setprio 0
	s_barrier
	s_add_i32 s54, s45, s23
	v_lshl_add_u64 v[220:221], s[30:31], 0, v[132:133]
	s_mov_b32 m0, s54
	ds_read_b128 v[204:207], v160
	ds_read_b128 v[208:211], v160 offset:1024
	ds_read_b128 v[212:215], v160 offset:2048
	ds_read_b128 v[216:219], v160 offset:3072
	global_load_lds_dwordx4 v[220:221], off
	v_lshl_add_u64 v[222:223], s[30:31], 0, v[128:129]
	s_add_i32 m0, s54, 0x2000
	s_nop 0
	global_load_lds_dwordx4 v[222:223], off
	s_barrier
	s_waitcnt lgkmcnt(0)
	s_setprio 1
	s_waitcnt lgkmcnt(0)
	v_mfma_f32_16x16x32_bf16 v[116:119], v[204:207], v[170:173], v[116:119]
	v_mfma_f32_16x16x32_bf16 v[112:115], v[212:215], v[170:173], v[112:115]
	v_mfma_f32_16x16x32_bf16 v[100:103], v[204:207], v[178:181], v[100:103]
	v_mfma_f32_16x16x32_bf16 v[96:99], v[212:215], v[178:181], v[96:99]
	v_mfma_f32_16x16x32_bf16 v[84:87], v[204:207], v[186:189], v[84:87]
	v_mfma_f32_16x16x32_bf16 v[80:83], v[212:215], v[186:189], v[80:83]
	v_mfma_f32_16x16x32_bf16 v[68:71], v[204:207], v[196:199], v[68:71]
	v_mfma_f32_16x16x32_bf16 v[64:67], v[212:215], v[196:199], v[64:67]
	v_mfma_f32_16x16x32_bf16 v[116:119], v[208:211], v[174:177], v[116:119]
	v_mfma_f32_16x16x32_bf16 v[112:115], v[216:219], v[174:177], v[112:115]
	v_mfma_f32_16x16x32_bf16 v[100:103], v[208:211], v[182:185], v[100:103]
	v_mfma_f32_16x16x32_bf16 v[96:99], v[216:219], v[182:185], v[96:99]
	v_mfma_f32_16x16x32_bf16 v[84:87], v[208:211], v[190:193], v[84:87]
	v_mfma_f32_16x16x32_bf16 v[80:83], v[216:219], v[190:193], v[80:83]
	v_mfma_f32_16x16x32_bf16 v[68:71], v[208:211], v[200:203], v[68:71]
	v_mfma_f32_16x16x32_bf16 v[64:67], v[216:219], v[200:203], v[64:67]
	s_setprio 0
	s_mov_b32 m0, s25
	v_lshl_add_u64 v[224:225], s[20:21], 0, v[134:135]
	s_barrier
	ds_read_b128 v[170:173], v159 offset:16384
	ds_read_b128 v[174:177], v159 offset:17408
	ds_read_b128 v[178:181], v159 offset:18432
	ds_read_b128 v[182:185], v159 offset:19456
	ds_read_b128 v[186:189], v159 offset:20480
	ds_read_b128 v[190:193], v159 offset:21504
	ds_read_b128 v[196:199], v159 offset:22528
	ds_read_b128 v[200:203], v159 offset:23552
	global_load_lds_dwordx4 v[224:225], off
	v_lshl_add_u64 v[226:227], s[20:21], 0, v[130:131]
	s_mov_b32 m0, s37
	s_nop 0
	global_load_lds_dwordx4 v[226:227], off
	s_barrier
	s_waitcnt lgkmcnt(0)
	s_setprio 1
	s_waitcnt lgkmcnt(0)
	v_mfma_f32_16x16x32_bf16 v[60:63], v[148:151], v[170:173], v[60:63]
	v_mfma_f32_16x16x32_bf16 v[56:59], v[162:165], v[170:173], v[56:59]
	v_mfma_f32_16x16x32_bf16 v[44:47], v[148:151], v[178:181], v[44:47]
	v_mfma_f32_16x16x32_bf16 v[40:43], v[162:165], v[178:181], v[40:43]
	v_mfma_f32_16x16x32_bf16 v[28:31], v[148:151], v[186:189], v[28:31]
	v_mfma_f32_16x16x32_bf16 v[24:27], v[162:165], v[186:189], v[24:27]
	v_mfma_f32_16x16x32_bf16 v[12:15], v[148:151], v[196:199], v[12:15]
	v_mfma_f32_16x16x32_bf16 v[8:11], v[162:165], v[196:199], v[8:11]
	v_mfma_f32_16x16x32_bf16 v[60:63], v[152:155], v[174:177], v[60:63]
	v_mfma_f32_16x16x32_bf16 v[56:59], v[166:169], v[174:177], v[56:59]
	v_mfma_f32_16x16x32_bf16 v[44:47], v[152:155], v[182:185], v[44:47]
	v_mfma_f32_16x16x32_bf16 v[40:43], v[166:169], v[182:185], v[40:43]
	v_mfma_f32_16x16x32_bf16 v[28:31], v[152:155], v[190:193], v[28:31]
	v_mfma_f32_16x16x32_bf16 v[24:27], v[166:169], v[190:193], v[24:27]
	v_mfma_f32_16x16x32_bf16 v[12:15], v[152:155], v[200:203], v[12:15]
	v_mfma_f32_16x16x32_bf16 v[8:11], v[166:169], v[200:203], v[8:11]
	s_setprio 0
	s_barrier
	s_add_u32 s54, s30, 0x200000
	s_addc_u32 s55, s31, 0
	s_add_i32 s56, s47, s23
	v_lshl_add_u64 v[148:149], s[54:55], 0, v[132:133]
	s_mov_b32 m0, s56
	s_nop 0
	global_load_lds_dwordx4 v[148:149], off
	v_lshl_add_u64 v[148:149], s[54:55], 0, v[128:129]
	s_add_i32 m0, s56, 0x2000
	s_nop 0
	global_load_lds_dwordx4 v[148:149], off
	s_waitcnt vmcnt(6)
	s_barrier
	s_setprio 1
	v_mfma_f32_16x16x32_bf16 v[52:55], v[204:207], v[170:173], v[52:55]
	v_mfma_f32_16x16x32_bf16 v[48:51], v[212:215], v[170:173], v[48:51]
	v_mfma_f32_16x16x32_bf16 v[36:39], v[204:207], v[178:181], v[36:39]
	v_mfma_f32_16x16x32_bf16 v[32:35], v[212:215], v[178:181], v[32:35]
	v_mfma_f32_16x16x32_bf16 v[20:23], v[204:207], v[186:189], v[20:23]
	v_mfma_f32_16x16x32_bf16 v[16:19], v[212:215], v[186:189], v[16:19]
	v_mfma_f32_16x16x32_bf16 v[4:7], v[204:207], v[196:199], v[4:7]
	v_mfma_f32_16x16x32_bf16 v[0:3], v[212:215], v[196:199], v[0:3]
	v_mfma_f32_16x16x32_bf16 v[52:55], v[208:211], v[174:177], v[52:55]
	v_mfma_f32_16x16x32_bf16 v[48:51], v[216:219], v[174:177], v[48:51]
	v_mfma_f32_16x16x32_bf16 v[36:39], v[208:211], v[182:185], v[36:39]
	v_mfma_f32_16x16x32_bf16 v[32:35], v[216:219], v[182:185], v[32:35]
	v_mfma_f32_16x16x32_bf16 v[20:23], v[208:211], v[190:193], v[20:23]
	v_mfma_f32_16x16x32_bf16 v[16:19], v[216:219], v[190:193], v[16:19]
	v_mfma_f32_16x16x32_bf16 v[4:7], v[208:211], v[200:203], v[4:7]
	v_mfma_f32_16x16x32_bf16 v[0:3], v[216:219], v[200:203], v[0:3]
	s_setprio 0
	s_add_i32 s54, 0, 0x18000
	v_add_u32_e32 v161, s54, v147
	s_barrier
	ds_read_b128 v[148:151], v161
	ds_read_b128 v[152:155], v161 offset:1024
	ds_read_b128 v[162:165], v161 offset:2048
	ds_read_b128 v[166:169], v161 offset:3072
	s_add_u32 s20, s20, 0x200000
	s_addc_u32 s21, s21, 0
	s_mov_b32 m0, s38
	v_lshl_add_u64 v[204:205], s[20:21], 0, v[134:135]
	ds_read_b128 v[170:173], v159 offset:32768
	ds_read_b128 v[174:177], v159 offset:33792
	ds_read_b128 v[178:181], v159 offset:34816
	ds_read_b128 v[182:185], v159 offset:35840
	ds_read_b128 v[186:189], v159 offset:36864
	ds_read_b128 v[190:193], v159 offset:37888
	ds_read_b128 v[196:199], v159 offset:38912
	ds_read_b128 v[200:203], v159 offset:39936
	global_load_lds_dwordx4 v[204:205], off
	v_lshl_add_u64 v[204:205], s[20:21], 0, v[130:131]
	s_mov_b32 m0, s39
	s_nop 0
	global_load_lds_dwordx4 v[204:205], off
	s_waitcnt lgkmcnt(8)
	s_barrier
	s_waitcnt lgkmcnt(0)
	s_setprio 1
	s_waitcnt lgkmcnt(0)
	v_mfma_f32_16x16x32_bf16 v[124:127], v[148:151], v[170:173], v[124:127]
	v_mfma_f32_16x16x32_bf16 v[120:123], v[162:165], v[170:173], v[120:123]
	v_mfma_f32_16x16x32_bf16 v[108:111], v[148:151], v[178:181], v[108:111]
	v_mfma_f32_16x16x32_bf16 v[104:107], v[162:165], v[178:181], v[104:107]
	v_mfma_f32_16x16x32_bf16 v[92:95], v[148:151], v[186:189], v[92:95]
	v_mfma_f32_16x16x32_bf16 v[88:91], v[162:165], v[186:189], v[88:91]
	v_mfma_f32_16x16x32_bf16 v[76:79], v[148:151], v[196:199], v[76:79]
	v_mfma_f32_16x16x32_bf16 v[72:75], v[162:165], v[196:199], v[72:75]
	v_mfma_f32_16x16x32_bf16 v[124:127], v[152:155], v[174:177], v[124:127]
	v_mfma_f32_16x16x32_bf16 v[120:123], v[166:169], v[174:177], v[120:123]
	v_mfma_f32_16x16x32_bf16 v[108:111], v[152:155], v[182:185], v[108:111]
	v_mfma_f32_16x16x32_bf16 v[104:107], v[166:169], v[182:185], v[104:107]
	v_mfma_f32_16x16x32_bf16 v[92:95], v[152:155], v[190:193], v[92:95]
	v_mfma_f32_16x16x32_bf16 v[88:91], v[166:169], v[190:193], v[88:91]
	v_mfma_f32_16x16x32_bf16 v[76:79], v[152:155], v[200:203], v[76:79]
	v_mfma_f32_16x16x32_bf16 v[72:75], v[166:169], v[200:203], v[72:75]
	s_setprio 0
	s_barrier
	s_add_i32 s55, 0, 0x1c000
	s_add_i32 s20, s54, s23
	v_add_u32_e32 v161, s55, v147
	v_lshl_add_u64 v[220:221], v[220:221], 0, s[8:9]
	s_mov_b32 m0, s20
	ds_read_b128 v[204:207], v161
	ds_read_b128 v[208:211], v161 offset:1024
	ds_read_b128 v[212:215], v161 offset:2048
	ds_read_b128 v[216:219], v161 offset:3072
	global_load_lds_dwordx4 v[220:221], off
	v_lshl_add_u64 v[220:221], v[222:223], 0, s[8:9]
	s_add_i32 m0, s20, 0x2000
	s_nop 0
	global_load_lds_dwordx4 v[220:221], off
	s_barrier
	s_waitcnt lgkmcnt(0)
	s_setprio 1
	s_waitcnt lgkmcnt(0)
	v_mfma_f32_16x16x32_bf16 v[116:119], v[204:207], v[170:173], v[116:119]
	v_mfma_f32_16x16x32_bf16 v[112:115], v[212:215], v[170:173], v[112:115]
	v_mfma_f32_16x16x32_bf16 v[100:103], v[204:207], v[178:181], v[100:103]
	v_mfma_f32_16x16x32_bf16 v[96:99], v[212:215], v[178:181], v[96:99]
	v_mfma_f32_16x16x32_bf16 v[84:87], v[204:207], v[186:189], v[84:87]
	v_mfma_f32_16x16x32_bf16 v[80:83], v[212:215], v[186:189], v[80:83]
	v_mfma_f32_16x16x32_bf16 v[68:71], v[204:207], v[196:199], v[68:71]
	v_mfma_f32_16x16x32_bf16 v[64:67], v[212:215], v[196:199], v[64:67]
	v_mfma_f32_16x16x32_bf16 v[116:119], v[208:211], v[174:177], v[116:119]
	v_mfma_f32_16x16x32_bf16 v[112:115], v[216:219], v[174:177], v[112:115]
	v_mfma_f32_16x16x32_bf16 v[100:103], v[208:211], v[182:185], v[100:103]
	v_mfma_f32_16x16x32_bf16 v[96:99], v[216:219], v[182:185], v[96:99]
	v_mfma_f32_16x16x32_bf16 v[84:87], v[208:211], v[190:193], v[84:87]
	v_mfma_f32_16x16x32_bf16 v[80:83], v[216:219], v[190:193], v[80:83]
	v_mfma_f32_16x16x32_bf16 v[68:71], v[208:211], v[200:203], v[68:71]
	v_mfma_f32_16x16x32_bf16 v[64:67], v[216:219], v[200:203], v[64:67]
	s_setprio 0
	s_mov_b32 m0, s35
	v_lshl_add_u64 v[220:221], v[224:225], 0, s[8:9]
	s_barrier
	ds_read_b128 v[170:173], v159 offset:49152
	ds_read_b128 v[174:177], v159 offset:50176
	ds_read_b128 v[178:181], v159 offset:51200
	ds_read_b128 v[182:185], v159 offset:52224
	ds_read_b128 v[186:189], v159 offset:53248
	ds_read_b128 v[190:193], v159 offset:54272
	ds_read_b128 v[196:199], v159 offset:55296
	ds_read_b128 v[200:203], v159 offset:56320
	global_load_lds_dwordx4 v[220:221], off
	v_lshl_add_u64 v[220:221], v[226:227], 0, s[8:9]
	s_mov_b32 m0, s41
	s_nop 0
	global_load_lds_dwordx4 v[220:221], off
	s_barrier
	s_waitcnt lgkmcnt(0)
	s_setprio 1
	s_waitcnt lgkmcnt(0)
	v_mfma_f32_16x16x32_bf16 v[60:63], v[148:151], v[170:173], v[60:63]
	v_mfma_f32_16x16x32_bf16 v[56:59], v[162:165], v[170:173], v[56:59]
	v_mfma_f32_16x16x32_bf16 v[44:47], v[148:151], v[178:181], v[44:47]
	v_mfma_f32_16x16x32_bf16 v[40:43], v[162:165], v[178:181], v[40:43]
	v_mfma_f32_16x16x32_bf16 v[28:31], v[148:151], v[186:189], v[28:31]
	v_mfma_f32_16x16x32_bf16 v[24:27], v[162:165], v[186:189], v[24:27]
	v_mfma_f32_16x16x32_bf16 v[12:15], v[148:151], v[196:199], v[12:15]
	v_mfma_f32_16x16x32_bf16 v[8:11], v[162:165], v[196:199], v[8:11]
	v_mfma_f32_16x16x32_bf16 v[60:63], v[152:155], v[174:177], v[60:63]
	v_mfma_f32_16x16x32_bf16 v[56:59], v[166:169], v[174:177], v[56:59]
	v_mfma_f32_16x16x32_bf16 v[44:47], v[152:155], v[182:185], v[44:47]
	v_mfma_f32_16x16x32_bf16 v[40:43], v[166:169], v[182:185], v[40:43]
	v_mfma_f32_16x16x32_bf16 v[28:31], v[152:155], v[190:193], v[28:31]
	v_mfma_f32_16x16x32_bf16 v[24:27], v[166:169], v[190:193], v[24:27]
	v_mfma_f32_16x16x32_bf16 v[12:15], v[152:155], v[200:203], v[12:15]
	v_mfma_f32_16x16x32_bf16 v[8:11], v[166:169], v[200:203], v[8:11]
	s_setprio 0
	s_barrier
	s_add_u32 s20, s30, 0x200080
	s_addc_u32 s21, s31, 0
	s_add_i32 s30, s55, s23
	v_lshl_add_u64 v[148:149], s[20:21], 0, v[132:133]
	s_mov_b32 m0, s30
	s_nop 0
	global_load_lds_dwordx4 v[148:149], off
	v_lshl_add_u64 v[148:149], s[20:21], 0, v[128:129]
	s_add_i32 m0, s30, 0x2000
	s_nop 0
	global_load_lds_dwordx4 v[148:149], off
	s_waitcnt vmcnt(6)
	s_barrier
	s_setprio 1
	v_mfma_f32_16x16x32_bf16 v[52:55], v[204:207], v[170:173], v[52:55]
	v_mfma_f32_16x16x32_bf16 v[48:51], v[212:215], v[170:173], v[48:51]
	v_mfma_f32_16x16x32_bf16 v[36:39], v[204:207], v[178:181], v[36:39]
	v_mfma_f32_16x16x32_bf16 v[32:35], v[212:215], v[178:181], v[32:35]
	v_mfma_f32_16x16x32_bf16 v[20:23], v[204:207], v[186:189], v[20:23]
	v_mfma_f32_16x16x32_bf16 v[16:19], v[212:215], v[186:189], v[16:19]
	v_mfma_f32_16x16x32_bf16 v[4:7], v[204:207], v[196:199], v[4:7]
	v_mfma_f32_16x16x32_bf16 v[0:3], v[212:215], v[196:199], v[0:3]
	v_mfma_f32_16x16x32_bf16 v[52:55], v[208:211], v[174:177], v[52:55]
	v_mfma_f32_16x16x32_bf16 v[48:51], v[216:219], v[174:177], v[48:51]
	v_mfma_f32_16x16x32_bf16 v[36:39], v[208:211], v[182:185], v[36:39]
	v_mfma_f32_16x16x32_bf16 v[32:35], v[216:219], v[182:185], v[32:35]
	v_mfma_f32_16x16x32_bf16 v[20:23], v[208:211], v[190:193], v[20:23]
	v_mfma_f32_16x16x32_bf16 v[16:19], v[216:219], v[190:193], v[16:19]
	v_mfma_f32_16x16x32_bf16 v[4:7], v[208:211], v[200:203], v[4:7]
	v_mfma_f32_16x16x32_bf16 v[0:3], v[216:219], v[200:203], v[0:3]
	s_setprio 0
	s_add_i32 s53, s53, 2
	s_add_u32 s26, s26, 0x100
	s_addc_u32 s27, s27, 0
	s_add_u32 s51, s51, 0x100
	s_addc_u32 s52, s52, 0
	s_cmpk_gt_u32 s53, 0x7d
	s_barrier
	s_cbranch_scc0 .LBB0_1433
	s_lshl_b32 s11, s24, 8
	s_add_i32 s11, s11, s34
	v_or_b32_e32 v154, s11, v145
	s_add_i32 s15, s11, 0xffffe000
	v_lshl_or_b32 v150, s33, 8, v157
	s_lshr_b32 s15, s15, 12
	v_lshlrev_b32_e32 v148, 12, v154
	s_add_i32 s15, s15, 1
	s_cmp_gt_i32 s11, s48
	s_cselect_b32 s15, s15, 0
	s_mul_i32 s15, s15, s46
	v_lshl_add_u32 v148, v150, 1, v148
	s_add_u32 s20, s6, s15
	s_addc_u32 s21, s7, 0
	v_lshlrev_b32_e32 v149, 2, v150
	s_nop 0
	global_load_dwordx4 v[196:199], v149, s[20:21]
	global_load_dwordx4 v[200:203], v149, s[20:21] offset:16
	global_load_dwordx4 v[204:207], v149, s[20:21] offset:512
	global_load_dwordx4 v[208:211], v149, s[20:21] offset:528
	global_load_dwordx4 v[212:215], v148, s[74:75]
	global_load_dwordx4 v[216:219], v148, s[74:75] offset:256
	v_add_u32_e32 v151, 0x10000, v148
	global_load_dwordx4 v[220:223], v151, s[74:75]
	global_load_dwordx4 v[224:227], v151, s[74:75] offset:256
	v_add_u32_e32 v151, 0x20000, v148
	global_load_dwordx4 v[164:167], v151, s[74:75]
	global_load_dwordx4 v[168:171], v151, s[74:75] offset:256
	v_add_u32_e32 v151, 0x30000, v148
	global_load_dwordx4 v[172:175], v151, s[74:75]
	global_load_dwordx4 v[176:179], v151, s[74:75] offset:256
	s_mov_b32 s33, s10
	s_mov_b32 s24, s14
	s_mov_b64 s[30:31], s[18:19]
	s_mov_b64 s[26:27], s[16:17]
	s_waitcnt vmcnt(0)
	v_lshlrev_b32_e32 v180, 16, v212
	v_and_b32_e32 v181, 0xffff0000, v212
	v_lshlrev_b32_e32 v182, 16, v213
	v_and_b32_e32 v183, 0xffff0000, v213
	v_lshlrev_b32_e32 v184, 16, v214
	v_and_b32_e32 v185, 0xffff0000, v214
	v_lshlrev_b32_e32 v186, 16, v215
	v_and_b32_e32 v187, 0xffff0000, v215
	v_pk_fma_f32 v[124:125], v[124:125], v[196:197], v[180:181]
	v_pk_fma_f32 v[126:127], v[126:127], v[198:199], v[182:183]
	v_pk_fma_f32 v[120:121], v[120:121], v[200:201], v[184:185]
	v_pk_fma_f32 v[122:123], v[122:123], v[202:203], v[186:187]
	v_cvt_pk_bf16_f32 v123, v122, v123
	v_cvt_pk_bf16_f32 v122, v120, v121
	v_cvt_pk_bf16_f32 v121, v126, v127
	v_cvt_pk_bf16_f32 v120, v124, v125
	global_store_dwordx4 v148, v[120:123], s[42:43]
	v_lshlrev_b32_e32 v180, 16, v216
	v_and_b32_e32 v181, 0xffff0000, v216
	v_lshlrev_b32_e32 v182, 16, v217
	v_and_b32_e32 v183, 0xffff0000, v217
	v_lshlrev_b32_e32 v184, 16, v218
	v_and_b32_e32 v185, 0xffff0000, v218
	v_lshlrev_b32_e32 v186, 16, v219
	v_and_b32_e32 v187, 0xffff0000, v219
	v_pk_fma_f32 v[116:117], v[116:117], v[204:205], v[180:181]
	v_pk_fma_f32 v[118:119], v[118:119], v[206:207], v[182:183]
	v_pk_fma_f32 v[112:113], v[112:113], v[208:209], v[184:185]
	v_pk_fma_f32 v[114:115], v[114:115], v[210:211], v[186:187]
	v_cvt_pk_bf16_f32 v115, v114, v115
	v_cvt_pk_bf16_f32 v114, v112, v113
	v_cvt_pk_bf16_f32 v113, v118, v119
	v_cvt_pk_bf16_f32 v112, v116, v117
	global_store_dwordx4 v148, v[112:115], s[42:43] offset:256
	v_lshlrev_b32_e32 v180, 16, v220
	v_and_b32_e32 v181, 0xffff0000, v220
	v_lshlrev_b32_e32 v182, 16, v221
	v_and_b32_e32 v183, 0xffff0000, v221
	v_lshlrev_b32_e32 v184, 16, v222
	v_and_b32_e32 v185, 0xffff0000, v222
	v_lshlrev_b32_e32 v186, 16, v223
	v_and_b32_e32 v187, 0xffff0000, v223
	v_pk_fma_f32 v[108:109], v[108:109], v[196:197], v[180:181]
	v_pk_fma_f32 v[110:111], v[110:111], v[198:199], v[182:183]
	v_pk_fma_f32 v[104:105], v[104:105], v[200:201], v[184:185]
	v_pk_fma_f32 v[106:107], v[106:107], v[202:203], v[186:187]
	v_cvt_pk_bf16_f32 v107, v106, v107
	v_cvt_pk_bf16_f32 v106, v104, v105
	v_cvt_pk_bf16_f32 v105, v110, v111
	v_cvt_pk_bf16_f32 v104, v108, v109
	v_add_u32_e32 v151, 0x10000, v148
	global_store_dwordx4 v151, v[104:107], s[42:43]
	v_lshlrev_b32_e32 v180, 16, v224
	v_and_b32_e32 v181, 0xffff0000, v224
	v_lshlrev_b32_e32 v182, 16, v225
	v_and_b32_e32 v183, 0xffff0000, v225
	v_lshlrev_b32_e32 v184, 16, v226
	v_and_b32_e32 v185, 0xffff0000, v226
	v_lshlrev_b32_e32 v186, 16, v227
	v_and_b32_e32 v187, 0xffff0000, v227
	v_pk_fma_f32 v[100:101], v[100:101], v[204:205], v[180:181]
	v_pk_fma_f32 v[102:103], v[102:103], v[206:207], v[182:183]
	v_pk_fma_f32 v[96:97], v[96:97], v[208:209], v[184:185]
	v_pk_fma_f32 v[98:99], v[98:99], v[210:211], v[186:187]
	v_cvt_pk_bf16_f32 v99, v98, v99
	v_cvt_pk_bf16_f32 v98, v96, v97
	v_cvt_pk_bf16_f32 v97, v102, v103
	v_cvt_pk_bf16_f32 v96, v100, v101
	v_add_u32_e32 v151, 0x10000, v148
	global_store_dwordx4 v151, v[96:99], s[42:43] offset:256
	v_add_u32_e32 v151, 0x80000, v148
	global_load_dwordx4 v[212:215], v151, s[74:75]
	global_load_dwordx4 v[216:219], v151, s[74:75] offset:256
	v_add_u32_e32 v151, 0x90000, v148
	global_load_dwordx4 v[220:223], v151, s[74:75]
	global_load_dwordx4 v[224:227], v151, s[74:75] offset:256
	v_lshlrev_b32_e32 v180, 16, v164
	v_and_b32_e32 v181, 0xffff0000, v164
	v_lshlrev_b32_e32 v182, 16, v165
	v_and_b32_e32 v183, 0xffff0000, v165
	v_lshlrev_b32_e32 v184, 16, v166
	v_and_b32_e32 v185, 0xffff0000, v166
	v_lshlrev_b32_e32 v186, 16, v167
	v_and_b32_e32 v187, 0xffff0000, v167
	v_pk_fma_f32 v[92:93], v[92:93], v[196:197], v[180:181]
	v_pk_fma_f32 v[94:95], v[94:95], v[198:199], v[182:183]
	v_pk_fma_f32 v[88:89], v[88:89], v[200:201], v[184:185]
	v_pk_fma_f32 v[90:91], v[90:91], v[202:203], v[186:187]
	v_cvt_pk_bf16_f32 v91, v90, v91
	v_cvt_pk_bf16_f32 v90, v88, v89
	v_cvt_pk_bf16_f32 v89, v94, v95
	v_cvt_pk_bf16_f32 v88, v92, v93
	v_add_u32_e32 v151, 0x20000, v148
	global_store_dwordx4 v151, v[88:91], s[42:43]
	v_lshlrev_b32_e32 v180, 16, v168
	v_and_b32_e32 v181, 0xffff0000, v168
	v_lshlrev_b32_e32 v182, 16, v169
	v_and_b32_e32 v183, 0xffff0000, v169
	v_lshlrev_b32_e32 v184, 16, v170
	v_and_b32_e32 v185, 0xffff0000, v170
	v_lshlrev_b32_e32 v186, 16, v171
	v_and_b32_e32 v187, 0xffff0000, v171
	v_pk_fma_f32 v[84:85], v[84:85], v[204:205], v[180:181]
	v_pk_fma_f32 v[86:87], v[86:87], v[206:207], v[182:183]
	v_pk_fma_f32 v[80:81], v[80:81], v[208:209], v[184:185]
	v_pk_fma_f32 v[82:83], v[82:83], v[210:211], v[186:187]
	v_cvt_pk_bf16_f32 v83, v82, v83
	v_cvt_pk_bf16_f32 v82, v80, v81
	v_cvt_pk_bf16_f32 v81, v86, v87
	v_cvt_pk_bf16_f32 v80, v84, v85
	v_add_u32_e32 v151, 0x20000, v148
	global_store_dwordx4 v151, v[80:83], s[42:43] offset:256
	v_lshlrev_b32_e32 v180, 16, v172
	v_and_b32_e32 v181, 0xffff0000, v172
	v_lshlrev_b32_e32 v182, 16, v173
	v_and_b32_e32 v183, 0xffff0000, v173
	v_lshlrev_b32_e32 v184, 16, v174
	v_and_b32_e32 v185, 0xffff0000, v174
	v_lshlrev_b32_e32 v186, 16, v175
	v_and_b32_e32 v187, 0xffff0000, v175
	v_pk_fma_f32 v[76:77], v[76:77], v[196:197], v[180:181]
	v_pk_fma_f32 v[78:79], v[78:79], v[198:199], v[182:183]
	v_pk_fma_f32 v[72:73], v[72:73], v[200:201], v[184:185]
	v_pk_fma_f32 v[74:75], v[74:75], v[202:203], v[186:187]
	v_cvt_pk_bf16_f32 v75, v74, v75
	v_cvt_pk_bf16_f32 v74, v72, v73
	v_cvt_pk_bf16_f32 v73, v78, v79
	v_cvt_pk_bf16_f32 v72, v76, v77
	v_add_u32_e32 v151, 0x30000, v148
	global_store_dwordx4 v151, v[72:75], s[42:43]
	v_lshlrev_b32_e32 v180, 16, v176
	v_and_b32_e32 v181, 0xffff0000, v176
	v_lshlrev_b32_e32 v182, 16, v177
	v_and_b32_e32 v183, 0xffff0000, v177
	v_lshlrev_b32_e32 v184, 16, v178
	v_and_b32_e32 v185, 0xffff0000, v178
	v_lshlrev_b32_e32 v186, 16, v179
	v_and_b32_e32 v187, 0xffff0000, v179
	v_pk_fma_f32 v[68:69], v[68:69], v[204:205], v[180:181]
	v_pk_fma_f32 v[70:71], v[70:71], v[206:207], v[182:183]
	v_pk_fma_f32 v[64:65], v[64:65], v[208:209], v[184:185]
	v_pk_fma_f32 v[66:67], v[66:67], v[210:211], v[186:187]
	v_cvt_pk_bf16_f32 v67, v66, v67
	v_cvt_pk_bf16_f32 v66, v64, v65
	v_cvt_pk_bf16_f32 v65, v70, v71
	v_cvt_pk_bf16_f32 v64, v68, v69
	v_add_u32_e32 v151, 0x30000, v148
	global_store_dwordx4 v151, v[64:67], s[42:43] offset:256
	v_add_u32_e32 v151, 0xa0000, v148
	global_load_dwordx4 v[164:167], v151, s[74:75]
	global_load_dwordx4 v[168:171], v151, s[74:75] offset:256
	v_add_u32_e32 v151, 0xb0000, v148
	global_load_dwordx4 v[172:175], v151, s[74:75]
	global_load_dwordx4 v[176:179], v151, s[74:75] offset:256
	s_waitcnt vmcnt(0)
	v_lshlrev_b32_e32 v180, 16, v212
	v_and_b32_e32 v181, 0xffff0000, v212
	v_lshlrev_b32_e32 v182, 16, v213
	v_and_b32_e32 v183, 0xffff0000, v213
	v_lshlrev_b32_e32 v184, 16, v214
	v_and_b32_e32 v185, 0xffff0000, v214
	v_lshlrev_b32_e32 v186, 16, v215
	v_and_b32_e32 v187, 0xffff0000, v215
	v_pk_fma_f32 v[60:61], v[60:61], v[196:197], v[180:181]
	v_pk_fma_f32 v[62:63], v[62:63], v[198:199], v[182:183]
	v_pk_fma_f32 v[56:57], v[56:57], v[200:201], v[184:185]
	v_pk_fma_f32 v[58:59], v[58:59], v[202:203], v[186:187]
	v_cvt_pk_bf16_f32 v59, v58, v59
	v_cvt_pk_bf16_f32 v58, v56, v57
	v_cvt_pk_bf16_f32 v57, v62, v63
	v_cvt_pk_bf16_f32 v56, v60, v61
	v_add_u32_e32 v151, 0x80000, v148
	global_store_dwordx4 v151, v[56:59], s[42:43]
	v_lshlrev_b32_e32 v180, 16, v216
	v_and_b32_e32 v181, 0xffff0000, v216
	v_lshlrev_b32_e32 v182, 16, v217
	v_and_b32_e32 v183, 0xffff0000, v217
	v_lshlrev_b32_e32 v184, 16, v218
	v_and_b32_e32 v185, 0xffff0000, v218
	v_lshlrev_b32_e32 v186, 16, v219
	v_and_b32_e32 v187, 0xffff0000, v219
	v_pk_fma_f32 v[52:53], v[52:53], v[204:205], v[180:181]
	v_pk_fma_f32 v[54:55], v[54:55], v[206:207], v[182:183]
	v_pk_fma_f32 v[48:49], v[48:49], v[208:209], v[184:185]
	v_pk_fma_f32 v[50:51], v[50:51], v[210:211], v[186:187]
	v_cvt_pk_bf16_f32 v51, v50, v51
	v_cvt_pk_bf16_f32 v50, v48, v49
	v_cvt_pk_bf16_f32 v49, v54, v55
	v_cvt_pk_bf16_f32 v48, v52, v53
	v_add_u32_e32 v151, 0x80000, v148
	global_store_dwordx4 v151, v[48:51], s[42:43] offset:256
	v_lshlrev_b32_e32 v180, 16, v220
	v_and_b32_e32 v181, 0xffff0000, v220
	v_lshlrev_b32_e32 v182, 16, v221
	v_and_b32_e32 v183, 0xffff0000, v221
	v_lshlrev_b32_e32 v184, 16, v222
	v_and_b32_e32 v185, 0xffff0000, v222
	v_lshlrev_b32_e32 v186, 16, v223
	v_and_b32_e32 v187, 0xffff0000, v223
	v_pk_fma_f32 v[44:45], v[44:45], v[196:197], v[180:181]
	v_pk_fma_f32 v[46:47], v[46:47], v[198:199], v[182:183]
	v_pk_fma_f32 v[40:41], v[40:41], v[200:201], v[184:185]
	v_pk_fma_f32 v[42:43], v[42:43], v[202:203], v[186:187]
	v_cvt_pk_bf16_f32 v43, v42, v43
	v_cvt_pk_bf16_f32 v42, v40, v41
	v_cvt_pk_bf16_f32 v41, v46, v47
	v_cvt_pk_bf16_f32 v40, v44, v45
	v_add_u32_e32 v151, 0x90000, v148
	global_store_dwordx4 v151, v[40:43], s[42:43]
	v_lshlrev_b32_e32 v180, 16, v224
	v_and_b32_e32 v181, 0xffff0000, v224
	v_lshlrev_b32_e32 v182, 16, v225
	v_and_b32_e32 v183, 0xffff0000, v225
	v_lshlrev_b32_e32 v184, 16, v226
	v_and_b32_e32 v185, 0xffff0000, v226
	v_lshlrev_b32_e32 v186, 16, v227
	v_and_b32_e32 v187, 0xffff0000, v227
	v_pk_fma_f32 v[36:37], v[36:37], v[204:205], v[180:181]
	v_pk_fma_f32 v[38:39], v[38:39], v[206:207], v[182:183]
	v_pk_fma_f32 v[32:33], v[32:33], v[208:209], v[184:185]
	v_pk_fma_f32 v[34:35], v[34:35], v[210:211], v[186:187]
	v_cvt_pk_bf16_f32 v35, v34, v35
	v_cvt_pk_bf16_f32 v34, v32, v33
	v_cvt_pk_bf16_f32 v33, v38, v39
	v_cvt_pk_bf16_f32 v32, v36, v37
	v_add_u32_e32 v151, 0x90000, v148
	global_store_dwordx4 v151, v[32:35], s[42:43] offset:256
	v_lshlrev_b32_e32 v180, 16, v164
	v_and_b32_e32 v181, 0xffff0000, v164
	v_lshlrev_b32_e32 v182, 16, v165
	v_and_b32_e32 v183, 0xffff0000, v165
	v_lshlrev_b32_e32 v184, 16, v166
	v_and_b32_e32 v185, 0xffff0000, v166
	v_lshlrev_b32_e32 v186, 16, v167
	v_and_b32_e32 v187, 0xffff0000, v167
	v_pk_fma_f32 v[28:29], v[28:29], v[196:197], v[180:181]
	v_pk_fma_f32 v[30:31], v[30:31], v[198:199], v[182:183]
	v_pk_fma_f32 v[24:25], v[24:25], v[200:201], v[184:185]
	v_pk_fma_f32 v[26:27], v[26:27], v[202:203], v[186:187]
	v_cvt_pk_bf16_f32 v27, v26, v27
	v_cvt_pk_bf16_f32 v26, v24, v25
	v_cvt_pk_bf16_f32 v25, v30, v31
	v_cvt_pk_bf16_f32 v24, v28, v29
	v_add_u32_e32 v151, 0xa0000, v148
	global_store_dwordx4 v151, v[24:27], s[42:43]
	v_lshlrev_b32_e32 v180, 16, v168
	v_and_b32_e32 v181, 0xffff0000, v168
	v_lshlrev_b32_e32 v182, 16, v169
	v_and_b32_e32 v183, 0xffff0000, v169
	v_lshlrev_b32_e32 v184, 16, v170
	v_and_b32_e32 v185, 0xffff0000, v170
	v_lshlrev_b32_e32 v186, 16, v171
	v_and_b32_e32 v187, 0xffff0000, v171
	v_pk_fma_f32 v[20:21], v[20:21], v[204:205], v[180:181]
	v_pk_fma_f32 v[22:23], v[22:23], v[206:207], v[182:183]
	v_pk_fma_f32 v[16:17], v[16:17], v[208:209], v[184:185]
	v_pk_fma_f32 v[18:19], v[18:19], v[210:211], v[186:187]
	v_cvt_pk_bf16_f32 v19, v18, v19
	v_cvt_pk_bf16_f32 v18, v16, v17
	v_cvt_pk_bf16_f32 v17, v22, v23
	v_cvt_pk_bf16_f32 v16, v20, v21
	v_add_u32_e32 v151, 0xa0000, v148
	global_store_dwordx4 v151, v[16:19], s[42:43] offset:256
	v_lshlrev_b32_e32 v180, 16, v172
	v_and_b32_e32 v181, 0xffff0000, v172
	v_lshlrev_b32_e32 v182, 16, v173
	v_and_b32_e32 v183, 0xffff0000, v173
	v_lshlrev_b32_e32 v184, 16, v174
	v_and_b32_e32 v185, 0xffff0000, v174
	v_lshlrev_b32_e32 v186, 16, v175
	v_and_b32_e32 v187, 0xffff0000, v175
	v_pk_fma_f32 v[12:13], v[12:13], v[196:197], v[180:181]
	v_pk_fma_f32 v[14:15], v[14:15], v[198:199], v[182:183]
	v_pk_fma_f32 v[8:9], v[8:9], v[200:201], v[184:185]
	v_pk_fma_f32 v[10:11], v[10:11], v[202:203], v[186:187]
	v_cvt_pk_bf16_f32 v11, v10, v11
	v_cvt_pk_bf16_f32 v10, v8, v9
	v_cvt_pk_bf16_f32 v9, v14, v15
	v_cvt_pk_bf16_f32 v8, v12, v13
	v_add_u32_e32 v151, 0xb0000, v148
	global_store_dwordx4 v151, v[8:11], s[42:43]
	v_lshlrev_b32_e32 v180, 16, v176
	v_and_b32_e32 v181, 0xffff0000, v176
	v_lshlrev_b32_e32 v182, 16, v177
	v_and_b32_e32 v183, 0xffff0000, v177
	v_lshlrev_b32_e32 v184, 16, v178
	v_and_b32_e32 v185, 0xffff0000, v178
	v_lshlrev_b32_e32 v186, 16, v179
	v_and_b32_e32 v187, 0xffff0000, v179
	v_pk_fma_f32 v[4:5], v[4:5], v[204:205], v[180:181]
	v_pk_fma_f32 v[6:7], v[6:7], v[206:207], v[182:183]
	v_pk_fma_f32 v[0:1], v[0:1], v[208:209], v[184:185]
	v_pk_fma_f32 v[2:3], v[2:3], v[210:211], v[186:187]
	v_cvt_pk_bf16_f32 v3, v2, v3
	v_cvt_pk_bf16_f32 v2, v0, v1
	v_cvt_pk_bf16_f32 v1, v6, v7
	v_cvt_pk_bf16_f32 v0, v4, v5
	v_add_u32_e32 v151, 0xb0000, v148
	global_store_dwordx4 v151, v[0:3], s[42:43] offset:256
	s_waitcnt vmcnt(0)
	s_and_b64 vcc, exec, s[0:1]
	s_cbranch_vccz .LBB0_1430
	s_waitcnt vmcnt(0)
	s_cmpk_gt_u32 s12, 0xff
	s_cbranch_scc1 .LBB0_1437
	s_barrier
